# attention phase: permute the unit order so the 32 workgroups of an XCD take 32 consecutive query blocks (neighbouring blocks share K/V tiles in that XCD's L2)
# speedup vs baseline: 1.0022x; 1.0022x over previous
.LBB0_739:
	s_andn2_b64 vcc, exec, s[0:1]
	s_cbranch_vccnz .LBB0_756
	s_cmp_lg_u32 s59, 10
	s_cbranch_scc1 .LBB0_755
	s_mov_b64 s[0:1], 0
	v_mov_b32_e32 v42, v202
	v_readlane_b32 s78, v251, 0
	s_cmpk_gt_i32 s78, 0x17ff
	s_cbranch_scc1 .LBB0_755
	s_add_u32 s6, s26, s0
	s_addc_u32 s7, s27, s1
	s_add_u32 s48, s6, 0x1b000000
	s_addc_u32 s49, s7, 0
	s_and_b32 s100, s78, 7
	s_lshl_b32 s100, s100, 5
	s_bfe_u32 s101, s78, 0x50003
	s_or_b32 s100, s100, s101
	s_and_b32 s101, s78, 0xffffff00
	s_or_b32 s100, s100, s101
	s_ashr_i32 s0, s78, 11
	s_lshl_b32 s5, s0, 1
	s_bfe_u32 s1, s100, 0x40007
	s_and_b32 s4, s100, 0x7f
	s_bfm_b32 s8, s5, 0
	s_lshl_b32 s0, s0, 4
	s_and_b32 s8, s8, s4
	s_lshr_b32 s4, s4, s5
	s_or_b32 s0, s0, s1
	s_lshr_b32 s5, 0x4000, s5
	s_ashr_i32 s1, s0, 31
	s_mul_i32 s5, s5, s8
	s_lshl_b64 s[0:1], s[0:1], 20
	s_lshl_b32 s5, s5, 6
	s_add_u32 s0, s0, s5
	s_addc_u32 s1, s1, 0
	s_lshl_b32 s8, s4, 7
	v_ashrrev_i32_e32 v136, 1, v42
	s_add_i32 s9, s8, 0xffffff80
	s_waitcnt vmcnt(0)
	v_add_u32_e32 v0, s9, v136
	s_lshl_b64 s[0:1], s[0:1], 1
	v_max_i32_e32 v0, 0, v0
	s_add_u32 s4, s48, s0
	v_lshlrev_b32_e32 v10, 5, v42
	s_addc_u32 s5, s49, s1
	s_waitcnt lgkmcnt(0)
	v_lshlrev_b64 v[2:3], 7, v[0:1]
	v_and_b32_e32 v0, 32, v10
	v_lshl_add_u64 v[2:3], s[4:5], 0, v[2:3]
	v_lshlrev_b32_e32 v128, 1, v0
	v_mov_b32_e32 v129, v1
	v_lshl_add_u64 v[2:3], v[2:3], 0, v[128:129]
	global_load_dwordx4 v[96:99], v[2:3], off offset:48
	global_load_dwordx4 v[100:103], v[2:3], off offset:32
	global_load_dwordx4 v[104:107], v[2:3], off offset:16
	global_load_dwordx4 v[112:115], v[2:3], off
	v_and_b32_e32 v137, -2, v136
	v_mov_b32_e32 v2, v1
	v_mov_b32_e32 v3, v1
	v_add_u32_e32 v8, s9, v137
	v_mov_b32_e32 v0, v1
	v_mov_b64_e32 v[110:111], v[2:3]
	v_mov_b64_e32 v[126:127], v[2:3]
	v_mov_b64_e32 v[118:119], v[2:3]
	v_mov_b64_e32 v[122:123], v[2:3]
	v_cmp_lt_i32_e32 vcc, -1, v8
	v_mov_b64_e32 v[108:109], v[0:1]
	v_mov_b64_e32 v[124:125], v[0:1]
	v_mov_b64_e32 v[116:117], v[0:1]
	v_mov_b64_e32 v[120:121], v[0:1]
	s_and_saveexec_b64 s[4:5], vcc
	s_cbranch_execz .LBB0_744
	s_add_u32 s10, s6, s0
	s_waitcnt lgkmcnt(0)
	v_mov_b32_e32 v9, v1
	s_addc_u32 s11, s7, s1
	v_lshlrev_b64 v[2:3], 7, v[8:9]
	v_lshl_add_u64 v[2:3], s[10:11], 0, v[2:3]
	v_and_b32_e32 v0, 0x60, v10
	v_lshl_add_u64 v[2:3], v[2:3], 0, v[0:1]
	s_mov_b64 s[10:11], 0x21000000
	v_lshl_add_u64 v[8:9], v[2:3], 0, s[10:11]
	v_add_co_u32_e32 v2, vcc, 0x21000000, v2
	s_nop 1
	v_addc_co_u32_e32 v3, vcc, 0, v3, vcc
	global_load_dwordx4 v[120:123], v[2:3], off
	global_load_dwordx4 v[108:111], v[8:9], off offset:144
	global_load_dwordx4 v[116:119], v[8:9], off offset:16
	global_load_dwordx4 v[124:127], v[8:9], off offset:128
.LBB0_744:
	s_or_b64 exec, exec, s[4:5]
	v_ashrrev_i32_e32 v49, 2, v42
	s_add_u32 s50, s6, 0xe000000
	v_bfi_b32 v138, -16, v49, v42
	s_addc_u32 s51, s7, 0
	v_add_u32_e32 v2, s8, v138
	s_add_u32 s0, s50, s0
	v_ashrrev_i32_e32 v3, 31, v2
	s_addc_u32 s1, s51, s1
	v_lshlrev_b64 v[2:3], 7, v[2:3]
	v_lshl_add_u64 v[2:3], s[0:1], 0, v[2:3]
	s_add_i32 s0, s78, s28
	s_cmpk_lt_i32 s0, 0x1800
	s_cselect_b32 s0, s0, s78
	s_and_b32 s100, s0, 7
	s_lshl_b32 s100, s100, 5
	s_bfe_u32 s101, s0, 0x50003
	s_or_b32 s100, s100, s101
	s_and_b32 s0, s0, 0xffffff00
	s_or_b32 s0, s0, s100
	s_ashr_i32 s1, s0, 11
	s_lshl_b32 s5, s1, 1
	s_bfe_u32 s4, s0, 0x40007
	s_and_b32 s0, s0, 0x7f
	s_bfm_b32 s8, s5, 0
	s_and_b32 s8, s8, s0
	s_lshr_b32 s9, s0, s5
	s_lshl_b32 s0, s1, 4
	s_or_b32 s0, s0, s4
	s_lshr_b32 s4, 0x4000, s5
	s_ashr_i32 s1, s0, 31
	s_mul_i32 s4, s4, s8
	s_lshl_b64 s[0:1], s[0:1], 20
	s_lshl_b32 s4, s4, 6
	s_add_u32 s0, s0, s4
	v_lshrrev_b32_e32 v0, 1, v42
	s_addc_u32 s1, s1, 0
	s_lshl_b32 s8, s9, 7
	v_and_b32_e32 v0, 24, v0
	s_add_i32 s9, s8, 0xffffff80
	v_lshlrev_b32_e32 v130, 1, v0
	v_mov_b32_e32 v131, v1
	v_add_u32_e32 v0, s9, v136
	s_lshl_b64 s[0:1], s[0:1], 1
	v_lshl_add_u64 v[2:3], v[2:3], 0, v[130:131]
	v_max_i32_e32 v0, 0, v0
	s_add_u32 s4, s48, s0
	global_load_dwordx4 v[88:91], v[2:3], off
	global_load_dwordx4 v[92:95], v[2:3], off offset:64
	s_addc_u32 s5, s49, s1
	v_lshlrev_b64 v[2:3], 7, v[0:1]
	v_lshl_add_u64 v[2:3], s[4:5], 0, v[2:3]
	v_lshl_add_u64 v[2:3], v[2:3], 0, v[128:129]
	s_waitcnt lgkmcnt(0)
	global_load_dwordx4 v[8:11], v[2:3], off offset:48
	global_load_dwordx4 v[12:15], v[2:3], off offset:32
	global_load_dwordx4 v[16:19], v[2:3], off offset:16
	global_load_dwordx4 v[20:23], v[2:3], off
	v_add_u32_e32 v40, s9, v137
	v_lshlrev_b32_e32 v0, 4, v42
	v_cmp_gt_i32_e32 vcc, 0, v40
	v_and_b32_e32 v132, 48, v0
	s_and_saveexec_b64 s[4:5], vcc
	s_xor_b64 s[4:5], exec, s[4:5]
	v_and_b32_e32 v0, 48, v0
	v_mov_b32_e32 v48, v0
	v_mov_b64_e32 v[132:133], v[0:1]
	s_or_saveexec_b64 s[4:5], s[4:5]
	v_mov_b32_e32 v2, v1
	v_mov_b32_e32 v3, v1
	v_mov_b32_e32 v0, v1
	v_mov_b64_e32 v[26:27], v[2:3]
	v_mov_b64_e32 v[38:39], v[2:3]
	v_mov_b64_e32 v[34:35], v[2:3]
	v_mov_b64_e32 v[30:31], v[2:3]
	v_mov_b64_e32 v[24:25], v[0:1]
	v_mov_b64_e32 v[36:37], v[0:1]
	v_mov_b64_e32 v[32:33], v[0:1]
	v_mov_b64_e32 v[28:29], v[0:1]
	s_xor_b64 exec, exec, s[4:5]
	s_cbranch_execz .LBB0_748
	s_add_u32 s10, s6, s0
	v_mov_b32_e32 v41, v1
	s_addc_u32 s11, s7, s1
	v_lshlrev_b64 v[2:3], 7, v[40:41]
	v_lshl_add_u64 v[2:3], s[10:11], 0, v[2:3]
	v_lshlrev_b32_e32 v0, 1, v132
	v_lshl_add_u64 v[2:3], v[2:3], 0, v[0:1]
	s_mov_b64 s[10:11], 0x21000000
	s_mov_b32 s9, 0x21000000
	v_lshl_add_u64 v[32:33], v[2:3], 0, s[10:11]
	v_add_co_u32_e32 v2, vcc, s9, v2
	v_mov_b32_e32 v133, v1
	s_nop 0
	v_addc_co_u32_e32 v3, vcc, 0, v3, vcc
	global_load_dwordx4 v[24:27], v[2:3], off
	global_load_dwordx4 v[28:31], v[32:33], off offset:144
	global_load_dwordx4 v[36:39], v[32:33], off offset:16
	s_nop 0
	global_load_dwordx4 v[32:35], v[32:33], off offset:128
	v_mov_b32_e32 v48, v132

.LBB0_750:
	s_waitcnt vmcnt(11)
	v_and_b32_e32 v0, 0xffff, v120
	s_waitcnt vmcnt(8)
	v_lshl_or_b32 v0, v124, 16, v0
	s_waitcnt lgkmcnt(0)
	s_barrier
	ds_write_b128 v139, v[112:115] offset:36864
	ds_write_b128 v139, v[104:107] offset:36880
	ds_write_b128 v139, v[100:103] offset:36896
	ds_write_b128 v139, v[96:99] offset:36912
	ds_write_b32 v164, v0
	v_lshrrev_b32_e32 v0, 16, v120
	s_mov_b32 s64, 0xffff0000
	v_and_or_b32 v0, v124, s64, v0
	ds_write_b32 v140, v0 offset:544
	v_and_b32_e32 v0, 0xffff, v121
	v_lshl_or_b32 v0, v125, 16, v0
	ds_write_b32 v164, v0 offset:1088
	v_lshrrev_b32_e32 v0, 16, v121
	v_and_or_b32 v0, v125, s64, v0
	ds_write_b32 v140, v0 offset:1632
	v_and_b32_e32 v0, 0xffff, v122
	v_lshl_or_b32 v0, v126, 16, v0
	ds_write_b32 v164, v0 offset:2176
	v_lshrrev_b32_e32 v0, 16, v122
	v_and_or_b32 v0, v126, s64, v0
	ds_write_b32 v140, v0 offset:2720
	v_and_b32_e32 v0, 0xffff, v123
	v_lshl_or_b32 v0, v127, 16, v0
	ds_write_b32 v164, v0 offset:3264
	v_lshrrev_b32_e32 v0, 16, v123
	v_and_or_b32 v0, v127, s64, v0
	ds_write_b32 v140, v0 offset:3808
	v_and_b32_e32 v0, 0xffff, v116
	v_lshl_or_b32 v0, v108, 16, v0
	ds_write_b32 v164, v0 offset:4352
	v_lshrrev_b32_e32 v0, 16, v116
	v_and_or_b32 v0, v108, s64, v0
	ds_write_b32 v140, v0 offset:4896
	v_and_b32_e32 v0, 0xffff, v117
	v_lshl_or_b32 v0, v109, 16, v0
	ds_write_b32 v164, v0 offset:5440
	v_lshrrev_b32_e32 v0, 16, v117
	v_and_or_b32 v0, v109, s64, v0
	ds_write_b32 v140, v0 offset:5984
	v_and_b32_e32 v0, 0xffff, v118
	v_lshl_or_b32 v0, v110, 16, v0
	ds_write_b32 v164, v0 offset:6528
	v_lshrrev_b32_e32 v0, 16, v118
	v_and_or_b32 v0, v110, s64, v0
	ds_write_b32 v140, v0 offset:7072
	v_and_b32_e32 v0, 0xffff, v119
	v_lshl_or_b32 v0, v111, 16, v0
	ds_write_b32 v164, v0 offset:7616
	v_lshrrev_b32_e32 v0, 16, v119
	v_and_or_b32 v0, v111, s64, v0
	s_add_i32 s64, s95, s78
	s_cmpk_lt_i32 s64, 0x1800
	s_cselect_b32 s64, s64, s78
	s_and_b32 s100, s64, 7
	s_lshl_b32 s100, s100, 5
	s_bfe_u32 s101, s64, 0x50003
	s_or_b32 s100, s100, s101
	s_and_b32 s64, s64, 0xffffff00
	s_or_b32 s64, s64, s100
	s_ashr_i32 s65, s64, 11
	s_lshl_b32 s69, s65, 1
	s_bfe_u32 s68, s64, 0x40007
	s_and_b32 s64, s64, 0x7f
	s_bfm_b32 s70, s69, 0
	s_and_b32 s70, s70, s64
	s_lshr_b32 s71, s64, s69
	s_lshl_b32 s64, s65, 4
	s_or_b32 s64, s64, s68
	s_lshr_b32 s68, 0x4000, s69
	s_ashr_i32 s65, s64, 31
	s_mul_i32 s68, s68, s70
	s_lshl_b64 s[64:65], s[64:65], 20
	s_lshl_b32 s68, s68, 6
	s_add_u32 s64, s64, s68
	s_addc_u32 s65, s65, 0
	s_lshl_b32 s68, s71, 7
	s_add_i32 s69, s68, 0xffffff80
	ds_write_b32 v140, v0 offset:8160
	v_add_u32_e32 v0, s69, v136
	s_lshl_b64 s[64:65], s[64:65], 1
	v_max_i32_e32 v0, 0, v0
	s_add_u32 s70, s48, s64
	s_addc_u32 s71, s49, s65
	v_lshlrev_b64 v[2:3], 7, v[0:1]
	v_lshl_add_u64 v[2:3], s[70:71], 0, v[2:3]
	v_mov_b32_e32 v129, v1
	s_waitcnt lgkmcnt(0)
	s_barrier
	v_lshl_add_u64 v[2:3], v[2:3], 0, v[128:129]
	global_load_dwordx4 v[48:51], v[2:3], off offset:48
	global_load_dwordx4 v[52:55], v[2:3], off offset:32
	global_load_dwordx4 v[56:59], v[2:3], off offset:16
	global_load_dwordx4 v[60:63], v[2:3], off
	v_mov_b32_e32 v2, v1
	v_mov_b32_e32 v3, v1
	v_add_u32_e32 v80, s69, v137
	v_mov_b32_e32 v0, v1
	v_mov_b64_e32 v[66:67], v[2:3]
	v_mov_b64_e32 v[70:71], v[2:3]
	v_mov_b64_e32 v[74:75], v[2:3]
	v_mov_b64_e32 v[78:79], v[2:3]
	v_cmp_lt_i32_e32 vcc, -1, v80
	v_mov_b64_e32 v[64:65], v[0:1]
	v_mov_b64_e32 v[68:69], v[0:1]
	v_mov_b64_e32 v[72:73], v[0:1]
	v_mov_b64_e32 v[76:77], v[0:1]
	s_and_saveexec_b64 s[70:71], vcc
	s_cbranch_execz .LBB0_752
	v_readlane_b32 s69, v254, 45
	s_add_u32 vcc_lo, s69, s64
	v_readlane_b32 s69, v254, 46
	v_mov_b32_e32 v81, v1
	s_addc_u32 vcc_hi, s69, s65
	v_lshlrev_b64 v[2:3], 7, v[80:81]
	v_lshl_add_u64 v[2:3], vcc, 0, v[2:3]
	v_lshl_add_u64 v[2:3], v[132:133], 1, v[2:3]
	global_load_dwordx4 v[68:71], v[2:3], off offset:16
	global_load_dwordx4 v[64:67], v[2:3], off
	global_load_dwordx4 v[76:79], v[2:3], off offset:144
	global_load_dwordx4 v[72:75], v[2:3], off offset:128
.LBB0_752:
	s_or_b64 exec, exec, s[70:71]
	s_and_b32 s100, s78, 7
	s_lshl_b32 s100, s100, 5
	s_bfe_u32 s101, s78, 0x50003
	s_or_b32 s100, s100, s101
	s_and_b32 s101, s78, 0xffffff00
	s_or_b32 s100, s100, s101
	s_ashr_i32 s70, s78, 11
	s_lshl_b32 vcc_lo, s70, 1
	s_and_b32 s69, s100, 0x7f
	s_bfm_b32 s71, vcc_lo, 0
	s_and_b32 s71, s71, s69
	s_bfe_u32 s79, s100, 0x40007
	s_lshr_b32 s72, s69, vcc_lo
	v_add_u32_e32 v2, s68, v138
	s_add_u32 s64, s50, s64
	v_ashrrev_i32_e32 v3, 31, v2
	s_addc_u32 s65, s51, s65
	v_lshlrev_b64 v[2:3], 7, v[2:3]
	v_lshl_add_u64 v[2:3], s[64:65], 0, v[2:3]
	v_mov_b32_e32 v131, v1
	v_lshl_add_u64 v[2:3], v[2:3], 0, v[130:131]
	global_load_dwordx4 v[80:83], v[2:3], off
	global_load_dwordx4 v[84:87], v[2:3], off offset:64
	ds_read_b128 v[96:99], v141 offset:36864
	ds_read_b128 v[100:103], v141 offset:36928
	s_waitcnt vmcnt(13) lgkmcnt(1)
	v_mfma_f32_16x16x32_bf16 v[96:99], v[96:99], v[88:91], 0
	v_lshl_add_u32 v0, s72, 7, v138
	s_cmp_lg_u32 s72, 0
	v_readlane_b32 s68, v255, 13
	s_waitcnt vmcnt(12) lgkmcnt(0)
	v_mfma_f32_16x16x32_bf16 v[152:155], v[100:103], v[92:95], v[96:99]
	ds_read_b128 v[100:103], v142 offset:36928
	v_lshlrev_b32_e32 v0, vcc_lo, v0
	s_cselect_b64 s[64:65], -1, 0
	ds_read_b128 v[96:99], v142 offset:36864
	s_waitcnt lgkmcnt(0)
	v_mfma_f32_16x16x32_bf16 v[96:99], v[96:99], v[88:91], 0
	v_readlane_b32 s69, v255, 14
	v_readlane_b32 vcc_lo, v254, 6
	s_or_b64 s[68:69], s[68:69], s[64:65]
	v_mfma_f32_16x16x32_bf16 v[124:127], v[100:103], v[92:95], v[96:99]
	ds_read_b128 v[100:103], v143 offset:36928
	v_readlane_b32 vcc_hi, v254, 7
	s_and_b64 vcc, vcc, s[68:69]
	s_nop 0
	ds_read_b128 v[96:99], v143 offset:36864
	s_waitcnt lgkmcnt(0)
	v_mfma_f32_16x16x32_bf16 v[96:99], v[96:99], v[88:91], 0
	v_readlane_b32 s68, v255, 15
	v_cndmask_b32_e32 v3, v213, v152, vcc
	v_readlane_b32 s69, v255, 16
	v_mfma_f32_16x16x32_bf16 v[120:123], v[100:103], v[92:95], v[96:99]
	ds_read_b128 v[100:103], v144 offset:36928
	v_readlane_b32 vcc_lo, v254, 12
	s_or_b64 s[68:69], s[68:69], s[64:65]
	s_nop 0
	ds_read_b128 v[96:99], v144 offset:36864
	s_waitcnt lgkmcnt(0)
	v_mfma_f32_16x16x32_bf16 v[96:99], v[96:99], v[88:91], 0
	v_readlane_b32 vcc_hi, v254, 13
	s_and_b64 vcc, vcc, s[68:69]
	s_mov_b32 s68, 0xff61b1e6
	v_mfma_f32_16x16x32_bf16 v[116:119], v[100:103], v[92:95], v[96:99]
	ds_read_b128 v[100:103], v145 offset:36928
	v_cndmask_b32_e32 v2, v213, v153, vcc
	v_readlane_b32 vcc_lo, v254, 14
	s_nop 0
	ds_read_b128 v[96:99], v145 offset:36864
	s_waitcnt lgkmcnt(0)
	v_mfma_f32_16x16x32_bf16 v[96:99], v[96:99], v[88:91], 0
	v_readlane_b32 vcc_hi, v254, 15
	ds_read_b128 v[160:163], v149 offset:36928
	v_mfma_f32_16x16x32_bf16 v[112:115], v[100:103], v[92:95], v[96:99]
	ds_read_b128 v[100:103], v146 offset:36928
	s_nop 3
	ds_read_b128 v[96:99], v146 offset:36864
	s_waitcnt lgkmcnt(0)
	v_mfma_f32_16x16x32_bf16 v[96:99], v[96:99], v[88:91], 0
	v_mfma_f32_16x16x32_bf16 v[108:111], v[100:103], v[92:95], v[96:99]
	ds_read_b128 v[100:103], v147 offset:36928
	s_nop 5
	ds_read_b128 v[96:99], v147 offset:36864
	s_waitcnt lgkmcnt(0)
	v_mfma_f32_16x16x32_bf16 v[96:99], v[96:99], v[88:91], 0
	v_mfma_f32_16x16x32_bf16 v[104:107], v[100:103], v[92:95], v[96:99]
	ds_read_b128 v[100:103], v148 offset:36928
	s_nop 5
	ds_read_b128 v[96:99], v148 offset:36864
	s_waitcnt lgkmcnt(0)
	v_mfma_f32_16x16x32_bf16 v[96:99], v[96:99], v[88:91], 0
	v_mfma_f32_16x16x32_bf16 v[100:103], v[100:103], v[92:95], v[96:99]
	s_nop 6
	ds_read_b128 v[96:99], v149 offset:36864
	s_waitcnt lgkmcnt(0)
	v_mfma_f32_16x16x32_bf16 v[96:99], v[96:99], v[88:91], 0
	v_mfma_f32_16x16x32_bf16 v[96:99], v[160:163], v[92:95], v[96:99]
	ds_read_b128 v[160:163], v150 offset:36864
	s_waitcnt lgkmcnt(0)
	v_mfma_f32_16x16x32_bf16 v[88:91], v[160:163], v[88:91], 0
	ds_read_b128 v[160:163], v150 offset:36928
	s_waitcnt lgkmcnt(0)
	v_mfma_f32_16x16x32_bf16 v[88:91], v[160:163], v[92:95], v[88:91]
	v_max3_f32 v94, v3, s68, v2
	v_readlane_b32 s68, v255, 17
	v_readlane_b32 s69, v255, 18
	s_or_b64 s[68:69], s[68:69], s[64:65]
	s_and_b64 vcc, vcc, s[68:69]
	v_readlane_b32 s68, v255, 19
	v_cndmask_b32_e32 v92, v213, v154, vcc
	v_readlane_b32 s69, v255, 20
	v_readlane_b32 vcc_lo, v254, 16
	s_or_b64 s[68:69], s[68:69], s[64:65]
	v_readlane_b32 vcc_hi, v254, 17
	s_and_b64 vcc, vcc, s[68:69]
	v_readlane_b32 s68, v255, 21
	v_cndmask_b32_e32 v93, v213, v155, vcc
	v_readlane_b32 s69, v255, 22
	v_readlane_b32 vcc_lo, v254, 18
	s_or_b64 s[68:69], s[68:69], s[64:65]
	v_readlane_b32 vcc_hi, v254, 19
	s_and_b64 vcc, vcc, s[68:69]
	v_readlane_b32 s68, v255, 23
	v_cndmask_b32_e32 v95, v213, v124, vcc
	v_readlane_b32 s69, v255, 24
	v_readlane_b32 vcc_lo, v254, 20
	s_or_b64 s[68:69], s[68:69], s[64:65]
	v_readlane_b32 vcc_hi, v254, 21
	s_and_b64 vcc, vcc, s[68:69]
	v_readlane_b32 s68, v255, 25
	v_max3_f32 v129, v94, v92, v93
	v_cndmask_b32_e32 v94, v213, v125, vcc
	v_readlane_b32 s69, v255, 26
	v_readlane_b32 vcc_lo, v254, 22
	s_or_b64 s[68:69], s[68:69], s[64:65]
	v_readlane_b32 vcc_hi, v254, 23
	s_and_b64 vcc, vcc, s[68:69]
	v_readlane_b32 s68, v255, 27
	v_cndmask_b32_e32 v124, v213, v126, vcc
	v_readlane_b32 s69, v255, 28
	v_readlane_b32 vcc_lo, v254, 24
	s_or_b64 s[68:69], s[68:69], s[64:65]
	v_readlane_b32 vcc_hi, v254, 25
	s_and_b64 vcc, vcc, s[68:69]
	v_readlane_b32 s68, v255, 29
	v_cndmask_b32_e32 v125, v213, v127, vcc
	v_readlane_b32 s69, v255, 30
	v_readlane_b32 vcc_lo, v254, 26
	s_or_b64 s[68:69], s[68:69], s[64:65]
	v_readlane_b32 vcc_hi, v254, 27
	s_and_b64 vcc, vcc, s[68:69]
	v_readlane_b32 s68, v255, 31
	v_cndmask_b32_e32 v126, v213, v120, vcc
	v_readlane_b32 s69, v255, 32
	v_readlane_b32 vcc_lo, v254, 28
	s_or_b64 s[68:69], s[68:69], s[64:65]
	v_readlane_b32 vcc_hi, v254, 29
	s_and_b64 vcc, vcc, s[68:69]
	v_readlane_b32 s68, v255, 33
	v_cndmask_b32_e32 v120, v213, v121, vcc
	v_readlane_b32 s69, v255, 34
	v_readlane_b32 vcc_lo, v254, 30
	s_or_b64 s[68:69], s[68:69], s[64:65]
	v_readlane_b32 vcc_hi, v254, 31
	s_and_b64 vcc, vcc, s[68:69]
	v_readlane_b32 s68, v255, 35
	v_cndmask_b32_e32 v121, v213, v122, vcc
	v_readlane_b32 s69, v255, 36
	v_readlane_b32 vcc_lo, v254, 32
	s_or_b64 s[68:69], s[68:69], s[64:65]
	v_readlane_b32 vcc_hi, v254, 33
	s_and_b64 vcc, vcc, s[68:69]
	v_readlane_b32 s68, v255, 37
	v_cndmask_b32_e32 v122, v213, v123, vcc
	v_readlane_b32 s69, v255, 38
	v_readlane_b32 vcc_lo, v254, 34
	s_or_b64 s[68:69], s[68:69], s[64:65]
	v_readlane_b32 vcc_hi, v254, 35
	s_and_b64 vcc, vcc, s[68:69]
	v_readlane_b32 s68, v255, 39
	v_cndmask_b32_e32 v123, v213, v116, vcc
	v_readlane_b32 s69, v255, 40
	v_readlane_b32 vcc_lo, v254, 36
	s_or_b64 s[68:69], s[68:69], s[64:65]
	v_readlane_b32 vcc_hi, v254, 37
	s_and_b64 vcc, vcc, s[68:69]
	v_readlane_b32 s68, v255, 41
	v_cndmask_b32_e32 v116, v213, v117, vcc
	v_readlane_b32 s69, v255, 42
	v_readlane_b32 vcc_lo, v254, 38
	s_or_b64 s[68:69], s[68:69], s[64:65]
	v_readlane_b32 vcc_hi, v254, 39
	s_and_b64 vcc, vcc, s[68:69]
	v_readlane_b32 s68, v255, 43
	v_cndmask_b32_e32 v117, v213, v118, vcc
	v_readlane_b32 s69, v255, 44
	v_readlane_b32 vcc_lo, v254, 40
	s_or_b64 s[68:69], s[68:69], s[64:65]
	v_readlane_b32 vcc_hi, v254, 41
	s_and_b64 vcc, vcc, s[68:69]
	v_readlane_b32 s68, v255, 45
	v_cndmask_b32_e32 v118, v213, v119, vcc
	v_readlane_b32 s69, v255, 46
	v_readlane_b32 vcc_lo, v254, 42
	s_or_b64 s[68:69], s[68:69], s[64:65]
	v_readlane_b32 vcc_hi, v254, 43
	s_and_b64 vcc, vcc, s[68:69]
	v_readlane_b32 s68, v255, 47
	v_cndmask_b32_e32 v119, v213, v112, vcc
	v_readlane_b32 s69, v255, 48
	v_readlane_b32 vcc_lo, v253, 54
	s_or_b64 s[68:69], s[68:69], s[64:65]
	v_readlane_b32 vcc_hi, v253, 55
	s_and_b64 vcc, vcc, s[68:69]
	v_readlane_b32 s68, v255, 49
	v_cndmask_b32_e32 v112, v213, v113, vcc
	v_readlane_b32 s69, v255, 50
	v_readlane_b32 vcc_lo, v253, 52
	s_or_b64 s[68:69], s[68:69], s[64:65]
	v_readlane_b32 vcc_hi, v253, 53
	s_and_b64 vcc, vcc, s[68:69]
	v_readlane_b32 s68, v255, 51
	v_cndmask_b32_e32 v113, v213, v114, vcc
	v_readlane_b32 s69, v255, 52
	v_readlane_b32 vcc_lo, v253, 49
	s_or_b64 s[68:69], s[68:69], s[64:65]
	v_readlane_b32 vcc_hi, v253, 50
	s_and_b64 vcc, vcc, s[68:69]
	s_or_b64 s[68:69], s[82:83], s[64:65]
	v_cndmask_b32_e32 v114, v213, v115, vcc
	v_readlane_b32 vcc_lo, v254, 0
	v_readlane_b32 vcc_hi, v254, 1
	s_and_b64 vcc, vcc, s[68:69]
	s_or_b64 s[68:69], s[84:85], s[64:65]
	v_cndmask_b32_e32 v115, v213, v108, vcc
	v_readlane_b32 vcc_lo, v253, 56
	v_readlane_b32 vcc_hi, v253, 57
	s_and_b64 vcc, vcc, s[68:69]
	s_or_b64 s[68:69], s[86:87], s[64:65]
	v_cndmask_b32_e32 v108, v213, v109, vcc
	v_readlane_b32 vcc_lo, v253, 58
	v_readlane_b32 vcc_hi, v253, 59
	s_and_b64 vcc, vcc, s[68:69]
	s_or_b64 s[68:69], s[88:89], s[64:65]
	v_cndmask_b32_e32 v109, v213, v110, vcc
	v_readlane_b32 vcc_lo, v253, 60
	v_readlane_b32 vcc_hi, v253, 61
	s_and_b64 vcc, vcc, s[68:69]
	s_or_b64 s[68:69], s[90:91], s[64:65]
	v_cndmask_b32_e32 v110, v213, v111, vcc
	v_readlane_b32 vcc_lo, v253, 62
	v_readlane_b32 vcc_hi, v253, 63
	s_and_b64 vcc, vcc, s[68:69]
	v_max3_f32 v129, v129, v95, v94
	v_cndmask_b32_e32 v111, v213, v104, vcc
	v_readlane_b32 vcc_lo, v254, 2
	s_or_b64 s[68:69], s[92:93], s[64:65]
	v_readlane_b32 vcc_hi, v254, 3
	v_max3_f32 v127, v129, v124, v125
	s_and_b64 vcc, vcc, s[68:69]
	v_max3_f32 v127, v127, v126, v120
	v_cndmask_b32_e32 v104, v213, v105, vcc
	v_readlane_b32 vcc_lo, v254, 47
	v_max3_f32 v127, v127, v121, v122
	s_or_b64 s[68:69], s[66:67], s[64:65]
	v_readlane_b32 vcc_hi, v254, 48
	v_max3_f32 v127, v127, v123, v116
	s_and_b64 vcc, vcc, s[68:69]
	v_max3_f32 v127, v127, v117, v118
	v_cndmask_b32_e32 v105, v213, v106, vcc
	v_readlane_b32 vcc_lo, v254, 49
	v_max3_f32 v127, v127, v119, v112
	s_or_b64 s[68:69], s[96:97], s[64:65]
	v_readlane_b32 vcc_hi, v254, 50
	v_max3_f32 v127, v127, v113, v114
	s_and_b64 vcc, vcc, s[68:69]
	v_max3_f32 v127, v127, v115, v108
	v_cndmask_b32_e32 v107, v213, v107, vcc
	v_readlane_b32 vcc_lo, v254, 51
	v_max3_f32 v127, v127, v109, v110
	s_or_b64 s[68:69], s[36:37], s[64:65]
	v_readlane_b32 vcc_hi, v254, 52
	v_max3_f32 v127, v127, v111, v104
	s_and_b64 vcc, vcc, s[68:69]
	v_max3_f32 v106, v127, v105, v107
	v_cndmask_b32_e32 v127, v213, v100, vcc
	v_readlane_b32 vcc_lo, v254, 53
	s_or_b64 s[68:69], s[0:1], s[64:65]
	v_readlane_b32 vcc_hi, v254, 54
	s_and_b64 vcc, vcc, s[68:69]
	s_or_b64 s[68:69], s[4:5], s[64:65]
	v_cndmask_b32_e32 v100, v213, v101, vcc
	v_readlane_b32 vcc_lo, v254, 55
	v_readlane_b32 vcc_hi, v254, 56
	s_and_b64 vcc, vcc, s[68:69]
	s_or_b64 s[68:69], s[6:7], s[64:65]
	v_cndmask_b32_e32 v101, v213, v102, vcc
	v_readlane_b32 vcc_lo, v254, 57
	v_readlane_b32 vcc_hi, v254, 58
	s_and_b64 vcc, vcc, s[68:69]
	s_or_b64 s[68:69], s[8:9], s[64:65]
	v_cndmask_b32_e32 v102, v213, v103, vcc
	v_readlane_b32 vcc_lo, v254, 59
	v_readlane_b32 vcc_hi, v254, 60
	s_and_b64 vcc, vcc, s[68:69]
	s_or_b64 s[68:69], s[10:11], s[64:65]
	v_cndmask_b32_e32 v103, v213, v96, vcc
	v_readlane_b32 vcc_lo, v254, 61
	v_readlane_b32 vcc_hi, v254, 62
	s_and_b64 vcc, vcc, s[68:69]
	s_or_b64 s[68:69], s[30:31], s[64:65]
	v_cndmask_b32_e32 v96, v213, v97, vcc
	v_readlane_b32 vcc_lo, v254, 63
	v_readlane_b32 vcc_hi, v255, 0
	s_and_b64 vcc, vcc, s[68:69]
	s_or_b64 s[68:69], s[34:35], s[64:65]
	v_cndmask_b32_e32 v97, v213, v98, vcc
	v_readlane_b32 vcc_lo, v255, 1
	v_readlane_b32 vcc_hi, v255, 2
	s_and_b64 vcc, vcc, s[68:69]
	s_or_b64 s[68:69], s[38:39], s[64:65]
	v_cndmask_b32_e32 v99, v213, v99, vcc
	v_readlane_b32 vcc_lo, v255, 3
	v_readlane_b32 vcc_hi, v255, 4
	s_and_b64 vcc, vcc, s[68:69]
	s_or_b64 s[68:69], s[40:41], s[64:65]
	v_cndmask_b32_e32 v129, v213, v88, vcc
	v_readlane_b32 vcc_lo, v255, 5
	v_readlane_b32 vcc_hi, v255, 6
	s_and_b64 vcc, vcc, s[68:69]
	v_max3_f32 v106, v106, v127, v100
	v_cndmask_b32_e32 v98, v213, v89, vcc
	v_readlane_b32 vcc_lo, v255, 7
	s_or_b64 s[68:69], s[42:43], s[64:65]
	v_readlane_b32 vcc_hi, v255, 8
	v_max3_f32 v106, v106, v101, v102
	s_and_b64 vcc, vcc, s[68:69]
	v_readlane_b32 s68, v255, 9
	v_max3_f32 v106, v106, v103, v96
	s_or_b64 s[64:65], s[44:45], s[64:65]
	v_readlane_b32 s69, v255, 10
	v_max3_f32 v106, v106, v97, v99
	v_cndmask_b32_e32 v90, v213, v90, vcc
	s_and_b64 vcc, s[68:69], s[64:65]
	v_max3_f32 v88, v106, v129, v98
	v_cndmask_b32_e32 v89, v213, v91, vcc
	v_cmp_lt_i32_e32 vcc, v209, v210
	v_max3_f32 v91, v88, v90, v89
	s_nop 0
	v_cndmask_b32_e32 v88, v208, v209, vcc
	v_lshlrev_b32_e32 v88, 2, v88
	ds_bpermute_b32 v106, v88, v91
	v_cmp_lt_i32_e32 vcc, v211, v210
	s_waitcnt lgkmcnt(0)
	v_max_f32_e32 v106, v106, v106
	v_max_f32_e32 v91, v91, v106
	v_cndmask_b32_e32 v106, v208, v211, vcc
	v_lshlrev_b32_e32 v131, 2, v106
	ds_bpermute_b32 v106, v131, v91
	s_waitcnt lgkmcnt(0)
	v_max_f32_e32 v106, v106, v106
	v_max_f32_e32 v106, v91, v106
	v_sub_f32_e32 v3, v3, v106
	v_mul_f32_e32 v3, 0x3fb8aa3b, v3
	v_sub_f32_e32 v2, v2, v106
	v_exp_f32_e32 v3, v3
	v_mul_f32_e32 v2, 0x3fb8aa3b, v2
	v_exp_f32_e32 v135, v2
	v_sub_f32_e32 v94, v94, v106
	v_add_f32_e32 v91, 0, v3
	v_mul_f32_e32 v94, 0x3fb8aa3b, v94
	v_add_f32_e32 v2, v135, v91
	v_sub_f32_e32 v91, v92, v106
	v_mul_f32_e32 v91, 0x3fb8aa3b, v91
	v_sub_f32_e32 v92, v93, v106
	v_exp_f32_e32 v91, v91
	v_mul_f32_e32 v92, 0x3fb8aa3b, v92
	v_sub_f32_e32 v93, v95, v106
	v_exp_f32_e32 v92, v92
	v_mul_f32_e32 v93, 0x3fb8aa3b, v93
	v_exp_f32_e32 v93, v93
	v_sub_f32_e32 v95, v124, v106
	v_exp_f32_e32 v94, v94
	v_mul_f32_e32 v95, 0x3fb8aa3b, v95
	v_sub_f32_e32 v124, v125, v106
	v_add_f32_e32 v2, v91, v2
	v_exp_f32_e32 v95, v95
	v_mul_f32_e32 v124, 0x3fb8aa3b, v124
	v_sub_f32_e32 v125, v126, v106
	v_add_f32_e32 v2, v92, v2
	v_exp_f32_e32 v124, v124
	v_mul_f32_e32 v125, 0x3fb8aa3b, v125
	v_sub_f32_e32 v120, v120, v106
	v_add_f32_e32 v2, v93, v2
	v_exp_f32_e32 v125, v125
	v_mul_f32_e32 v120, 0x3fb8aa3b, v120
	v_sub_f32_e32 v121, v121, v106
	v_add_f32_e32 v2, v94, v2
	v_exp_f32_e32 v120, v120
	v_mul_f32_e32 v121, 0x3fb8aa3b, v121
	v_sub_f32_e32 v122, v122, v106
	v_add_f32_e32 v2, v95, v2
	v_exp_f32_e32 v121, v121
	v_mul_f32_e32 v122, 0x3fb8aa3b, v122
	v_sub_f32_e32 v123, v123, v106
	v_add_f32_e32 v2, v124, v2
	v_exp_f32_e32 v122, v122
	v_mul_f32_e32 v123, 0x3fb8aa3b, v123
	v_sub_f32_e32 v116, v116, v106
	v_add_f32_e32 v2, v125, v2
	v_exp_f32_e32 v123, v123
	v_mul_f32_e32 v116, 0x3fb8aa3b, v116
	v_sub_f32_e32 v117, v117, v106
	v_sub_f32_e32 v112, v112, v106
	v_add_f32_e32 v2, v120, v2
	v_exp_f32_e32 v116, v116
	v_mul_f32_e32 v117, 0x3fb8aa3b, v117
	v_sub_f32_e32 v118, v118, v106
	v_mul_f32_e32 v112, 0x3fb8aa3b, v112
	v_add_f32_e32 v2, v121, v2
	v_exp_f32_e32 v117, v117
	v_mul_f32_e32 v118, 0x3fb8aa3b, v118
	v_sub_f32_e32 v119, v119, v106
	v_exp_f32_e32 v126, v112
	v_sub_f32_e32 v112, v113, v106
	v_add_f32_e32 v2, v122, v2
	v_exp_f32_e32 v118, v118
	v_mul_f32_e32 v119, 0x3fb8aa3b, v119
	v_mul_f32_e32 v112, 0x3fb8aa3b, v112
	v_add_f32_e32 v2, v123, v2
	v_exp_f32_e32 v119, v119
	v_exp_f32_e32 v152, v112
	v_sub_f32_e32 v112, v114, v106
	v_sub_f32_e32 v108, v108, v106
	v_add_f32_e32 v2, v116, v2
	v_mul_f32_e32 v112, 0x3fb8aa3b, v112
	v_mul_f32_e32 v108, 0x3fb8aa3b, v108
	v_add_f32_e32 v2, v117, v2
	v_exp_f32_e32 v153, v112
	v_sub_f32_e32 v112, v115, v106
	v_exp_f32_e32 v155, v108
	v_sub_f32_e32 v108, v109, v106
	v_add_f32_e32 v2, v118, v2
	v_mul_f32_e32 v112, 0x3fb8aa3b, v112
	v_mul_f32_e32 v108, 0x3fb8aa3b, v108
	v_add_f32_e32 v2, v119, v2
	v_exp_f32_e32 v154, v112
	v_exp_f32_e32 v160, v108
	v_sub_f32_e32 v108, v110, v106
	v_add_f32_e32 v2, v126, v2
	v_mul_f32_e32 v108, 0x3fb8aa3b, v108
	v_add_f32_e32 v2, v152, v2
	v_exp_f32_e32 v161, v108
	v_sub_f32_e32 v108, v111, v106
	v_add_f32_e32 v2, v153, v2
	v_mul_f32_e32 v108, 0x3fb8aa3b, v108
	v_sub_f32_e32 v104, v104, v106
	v_add_f32_e32 v2, v154, v2
	v_exp_f32_e32 v162, v108
	v_mul_f32_e32 v104, 0x3fb8aa3b, v104
	v_sub_f32_e32 v105, v105, v106
	v_sub_f32_e32 v100, v100, v106
	v_add_f32_e32 v2, v155, v2
	v_exp_f32_e32 v104, v104
	v_mul_f32_e32 v105, 0x3fb8aa3b, v105
	v_sub_f32_e32 v107, v107, v106
	v_mul_f32_e32 v100, 0x3fb8aa3b, v100
	v_add_f32_e32 v2, v160, v2
	v_exp_f32_e32 v105, v105
	v_mul_f32_e32 v107, 0x3fb8aa3b, v107
	v_sub_f32_e32 v108, v127, v106
	v_exp_f32_e32 v163, v100
	v_sub_f32_e32 v100, v101, v106
	v_add_f32_e32 v2, v161, v2
	v_exp_f32_e32 v107, v107
	v_mul_f32_e32 v108, 0x3fb8aa3b, v108
	v_mul_f32_e32 v100, 0x3fb8aa3b, v100
	v_sub_f32_e32 v96, v96, v106
	v_add_f32_e32 v2, v162, v2
	v_exp_f32_e32 v127, v108
	v_exp_f32_e32 v165, v100
	v_sub_f32_e32 v100, v102, v106
	v_mul_f32_e32 v96, 0x3fb8aa3b, v96
	v_add_f32_e32 v2, v104, v2
	v_mul_f32_e32 v100, 0x3fb8aa3b, v100
	v_exp_f32_e32 v168, v96
	v_sub_f32_e32 v96, v97, v106
	v_add_f32_e32 v2, v105, v2
	v_exp_f32_e32 v166, v100
	v_sub_f32_e32 v100, v103, v106
	v_mul_f32_e32 v96, 0x3fb8aa3b, v96
	v_add_f32_e32 v2, v107, v2
	v_mul_f32_e32 v100, 0x3fb8aa3b, v100
	v_exp_f32_e32 v169, v96
	v_sub_f32_e32 v96, v99, v106
	v_add_f32_e32 v2, v127, v2
	v_exp_f32_e32 v167, v100
	v_mul_f32_e32 v96, 0x3fb8aa3b, v96
	v_add_f32_e32 v2, v163, v2
	v_exp_f32_e32 v170, v96
	v_sub_f32_e32 v96, v129, v106
	v_add_f32_e32 v2, v165, v2
	v_mul_f32_e32 v96, 0x3fb8aa3b, v96
	v_add_f32_e32 v2, v166, v2
	v_exp_f32_e32 v129, v96
	v_sub_f32_e32 v96, v98, v106
	v_add_f32_e32 v2, v167, v2
	v_mul_f32_e32 v96, 0x3fb8aa3b, v96
	v_sub_f32_e32 v90, v90, v106
	v_add_f32_e32 v2, v168, v2
	v_exp_f32_e32 v171, v96
	v_mul_f32_e32 v90, 0x3fb8aa3b, v90
	v_sub_f32_e32 v89, v89, v106
	v_add_f32_e32 v2, v169, v2
	v_exp_f32_e32 v172, v90
	v_mul_f32_e32 v89, 0x3fb8aa3b, v89
	v_add_f32_e32 v2, v170, v2
	v_exp_f32_e32 v173, v89
	v_add_f32_e32 v2, v129, v2
	v_add_f32_e32 v2, v171, v2
	v_add_f32_e32 v2, v172, v2
	v_add_f32_e32 v2, v173, v2
	ds_bpermute_b32 v88, v88, v2
	v_cvt_pk_bf16_f32 v89, v91, v92
	v_cvt_pk_bf16_f32 v90, v93, v94
	v_cvt_pk_bf16_f32 v91, v95, v124
	ds_read2_b64 v[92:95], v151 offset1:4
	s_waitcnt lgkmcnt(1)
	v_add_f32_e32 v174, v2, v88
	v_add_u32_e32 v2, s71, v0
	v_cvt_pk_bf16_f32 v88, v3, v135
	v_add_u32_e32 v0, 0x2000, v151
	v_add_u32_e32 v3, 0x4000, v151
	v_add_u32_e32 v124, 0x6000, v151
	ds_read2_b64 v[96:99], v0 offset0:68 offset1:72
	ds_read2_b64 v[100:103], v3 offset0:136 offset1:140
	ds_read2_b64 v[108:111], v124 offset0:204 offset1:208
	ds_read2_b64 v[112:115], v151 offset0:8 offset1:12
	s_waitcnt lgkmcnt(4)
	v_mfma_f32_16x16x32_bf16 v[92:95], v[92:95], v[88:91], 0
	ds_bpermute_b32 v131, v131, v174
	s_ashr_i32 s71, s70, 31
	v_mov_b32_e32 v135, v1
	s_waitcnt lgkmcnt(4)
	v_mfma_f32_16x16x32_bf16 v[96:99], v[96:99], v[88:91], 0
	s_waitcnt lgkmcnt(3)
	v_mfma_f32_16x16x32_bf16 v[100:103], v[100:103], v[88:91], 0
	s_waitcnt lgkmcnt(2)
	v_mfma_f32_16x16x32_bf16 v[88:91], v[108:111], v[88:91], 0
	v_cvt_pk_bf16_f32 v108, v125, v120
	v_cvt_pk_bf16_f32 v109, v121, v122
	v_cvt_pk_bf16_f32 v110, v123, v116
	v_cvt_pk_bf16_f32 v111, v117, v118
	s_waitcnt lgkmcnt(1)
	s_nop 0
	v_mfma_f32_16x16x32_bf16 v[92:95], v[112:115], v[108:111], v[92:95]
	ds_read2_b64 v[112:115], v0 offset0:76 offset1:80
	s_waitcnt lgkmcnt(0)
	v_mfma_f32_16x16x32_bf16 v[96:99], v[112:115], v[108:111], v[96:99]
	ds_read2_b64 v[112:115], v3 offset0:144 offset1:148
	s_waitcnt lgkmcnt(0)
	v_mfma_f32_16x16x32_bf16 v[100:103], v[112:115], v[108:111], v[100:103]
	ds_read2_b64 v[112:115], v124 offset0:212 offset1:216
	s_waitcnt lgkmcnt(0)
	v_mfma_f32_16x16x32_bf16 v[88:91], v[112:115], v[108:111], v[88:91]
	ds_read2_b64 v[112:115], v151 offset0:16 offset1:20
	v_cvt_pk_bf16_f32 v108, v119, v126
	v_cvt_pk_bf16_f32 v109, v152, v153
	v_cvt_pk_bf16_f32 v110, v154, v155
	v_cvt_pk_bf16_f32 v111, v160, v161
	s_waitcnt lgkmcnt(0)
	s_nop 0
	v_mfma_f32_16x16x32_bf16 v[92:95], v[112:115], v[108:111], v[92:95]
	ds_read2_b64 v[112:115], v0 offset0:84 offset1:88
	s_waitcnt lgkmcnt(0)
	v_mfma_f32_16x16x32_bf16 v[96:99], v[112:115], v[108:111], v[96:99]
	ds_read2_b64 v[112:115], v3 offset0:152 offset1:156
	s_waitcnt lgkmcnt(0)
	v_mfma_f32_16x16x32_bf16 v[100:103], v[112:115], v[108:111], v[100:103]
	ds_read2_b64 v[112:115], v124 offset0:220 offset1:224
	s_waitcnt lgkmcnt(0)
	v_mfma_f32_16x16x32_bf16 v[88:91], v[112:115], v[108:111], v[88:91]
	ds_read2_b64 v[112:115], v151 offset0:24 offset1:28
	v_cvt_pk_bf16_f32 v108, v162, v104
	v_cvt_pk_bf16_f32 v109, v105, v107
	v_cvt_pk_bf16_f32 v110, v127, v163
	v_cvt_pk_bf16_f32 v111, v165, v166
	v_add_f32_e32 v107, v174, v131
	s_waitcnt lgkmcnt(0)
	v_mfma_f32_16x16x32_bf16 v[92:95], v[112:115], v[108:111], v[92:95]
	ds_read2_b64 v[112:115], v0 offset0:92 offset1:96
	s_waitcnt lgkmcnt(0)
	v_mfma_f32_16x16x32_bf16 v[96:99], v[112:115], v[108:111], v[96:99]
	ds_read2_b64 v[112:115], v3 offset0:160 offset1:164
	s_waitcnt lgkmcnt(0)
	v_mfma_f32_16x16x32_bf16 v[112:115], v[112:115], v[108:111], v[100:103]
	s_nop 2
	ds_read2_b64 v[100:103], v124 offset0:228 offset1:232
	s_waitcnt lgkmcnt(0)
	v_mfma_f32_16x16x32_bf16 v[88:91], v[100:103], v[108:111], v[88:91]
	ds_read2_b64 v[100:103], v151 offset0:32 offset1:36
	v_cvt_pk_bf16_f32 v108, v167, v168
	v_cvt_pk_bf16_f32 v109, v169, v170
	v_cvt_pk_bf16_f32 v110, v129, v171
	v_cvt_pk_bf16_f32 v111, v172, v173
	s_waitcnt lgkmcnt(0)
	s_nop 0
	v_mfma_f32_16x16x32_bf16 v[100:103], v[100:103], v[108:111], v[92:95]
	s_nop 2
	ds_read2_b64 v[92:95], v0 offset0:100 offset1:104
	v_div_scale_f32 v0, s[64:65], v107, v107, 1.0
	s_waitcnt lgkmcnt(0)
	v_mfma_f32_16x16x32_bf16 v[96:99], v[92:95], v[108:111], v[96:99]
	ds_read2_b64 v[92:95], v3 offset0:168 offset1:172
	v_rcp_f32_e32 v3, v0
	s_lshl_b64 s[64:65], s[70:71], 25
	s_waitcnt lgkmcnt(0)
	v_mfma_f32_16x16x32_bf16 v[92:95], v[92:95], v[108:111], v[112:115]
	s_nop 2
	ds_read2_b64 v[112:115], v124 offset0:236 offset1:240
	v_fma_f32 v104, -v0, v3, 1.0
	v_fmac_f32_e32 v3, v104, v3
	v_div_scale_f32 v104, vcc, 1.0, v107, 1.0
	v_mul_f32_e32 v105, v104, v3
	s_waitcnt lgkmcnt(0)
	v_mfma_f32_16x16x32_bf16 v[88:91], v[112:115], v[108:111], v[88:91]
	v_fma_f32 v108, -v0, v105, v104
	v_fmac_f32_e32 v105, v108, v3
	v_fma_f32 v0, -v0, v105, v104
	v_div_fmas_f32 v0, v0, v3, v105
	s_add_u32 s64, s52, s64
	v_ashrrev_i32_e32 v3, 31, v2
	s_addc_u32 s65, s53, s65
	v_lshlrev_b64 v[104:105], 11, v[2:3]
	v_div_fixup_f32 v0, v0, v107, 1.0
	v_lshl_add_u64 v[104:105], s[64:65], 0, v[104:105]
	s_lshl_b32 s72, s79, 7
	v_lshl_add_u64 v[104:105], v[104:105], 0, s[72:73]
	v_pk_mul_f32 v[100:101], v[0:1], v[100:101] op_sel_hi:[0,1]
	v_pk_mul_f32 v[102:103], v[0:1], v[102:103] op_sel_hi:[0,1]
	v_pk_mul_f32 v[96:97], v[0:1], v[96:97] op_sel_hi:[0,1]
	v_pk_mul_f32 v[98:99], v[0:1], v[98:99] op_sel_hi:[0,1]
	v_pk_mul_f32 v[92:93], v[0:1], v[92:93] op_sel_hi:[0,1]
	v_pk_mul_f32 v[94:95], v[0:1], v[94:95] op_sel_hi:[0,1]
	v_pk_mul_f32 v[88:89], v[0:1], v[88:89] op_sel_hi:[0,1]
	v_pk_mul_f32 v[90:91], v[0:1], v[90:91] op_sel_hi:[0,1]
	v_lshl_add_u64 v[104:105], v[104:105], 0, v[134:135]
	v_cvt_pk_bf16_f32 v100, v100, v101
	v_cvt_pk_bf16_f32 v101, v102, v103
	v_cvt_pk_bf16_f32 v96, v96, v97
	v_cvt_pk_bf16_f32 v97, v98, v99
	v_cvt_pk_bf16_f32 v92, v92, v93
	v_cvt_pk_bf16_f32 v93, v94, v95
	v_cvt_pk_bf16_f32 v88, v88, v89
	v_cvt_pk_bf16_f32 v89, v90, v91
	global_store_dwordx2 v[104:105], v[100:101], off
	global_store_dwordx2 v[104:105], v[96:97], off offset:32
	global_store_dwordx2 v[104:105], v[92:93], off offset:64
	global_store_dwordx2 v[104:105], v[88:89], off offset:96
	s_mov_b64 s[64:65], exec
	v_readlane_b32 s68, v255, 11
	v_readlane_b32 s69, v255, 12
	s_and_b64 s[68:69], s[64:65], s[68:69]
	s_mov_b64 exec, s[68:69]
	s_cbranch_execz .LBB0_749
	s_mov_b32 s68, 0x800000
	v_cmp_gt_f32_e32 vcc, s68, v107
	s_mov_b32 s68, 0x3f317217
	v_lshlrev_b64 v[2:3], 6, v[2:3]
	v_cndmask_b32_e64 v0, 0, 32, vcc
	v_ldexp_f32 v0, v107, v0
	v_log_f32_e32 v0, v0
	v_cndmask_b32_e32 v88, 0, v212, vcc
	v_mul_f32_e32 v89, 0x3f317217, v0
	v_fma_f32 v89, v0, s68, -v89
	s_mov_b32 s68, 0x7f800000
	v_fmac_f32_e32 v89, 0x3377d1cf, v0
	v_cmp_lt_f32_e64 vcc, |v0|, s68
	s_lshl_b64 s[68:69], s[70:71], 20
	v_fmac_f32_e32 v89, 0x3f317217, v0
	s_add_u32 s68, s55, s68
	v_readlane_b32 s70, v254, 44
	v_cndmask_b32_e32 v0, v0, v89, vcc
	s_addc_u32 s69, s70, s69
	v_sub_f32_e32 v0, v0, v88
	v_lshl_add_u64 v[2:3], s[68:69], 0, v[2:3]
	s_lshl_b32 s72, s79, 2
	v_add_f32_e32 v0, v106, v0
	v_lshl_add_u64 v[2:3], v[2:3], 0, s[72:73]
	global_store_dword v[2:3], v0, off
	s_branch .LBB0_749
